# RWKV scan y-store: full DPP add + one ds_write2_b32 under exec mask instead of mov_dpp/branch/2 adds/2 address adds/2 ds_write (6 fewer instructions per timestep on the scan critical path)
# speedup vs baseline: 1.0048x; 1.0048x over previous
.LBB0_764:
	v_pk_mul_f32 v[104:105], v[38:39], v[86:87]
	v_pk_mul_f32 v[38:39], v[38:39], v[94:95]
	v_pk_mul_f32 v[106:107], v[34:35], v[90:91]
	v_pk_mul_f32 v[34:35], v[34:35], v[98:99]
	v_pk_fma_f32 v[104:105], v[40:41], v[88:89], v[104:105]
	v_pk_fma_f32 v[38:39], v[40:41], v[96:97], v[38:39]
	v_pk_fma_f32 v[40:41], v[36:37], v[92:93], v[106:107]
	v_pk_fma_f32 v[34:35], v[36:37], v[100:101], v[34:35]
	v_pk_add_f32 v[36:37], v[40:41], v[104:105]
	v_pk_add_f32 v[34:35], v[34:35], v[38:39]
	v_add_u32_e32 v116, 0, v114
	v_add_f32_e32 v36, v36, v37
	v_add_f32_e32 v34, v34, v35
	ds_read_b128 v[54:57], v116
	ds_read_b128 v[50:53], v116 offset:16
	ds_read_b128 v[78:81], v116 offset:256
	ds_read_b128 v[74:77], v116 offset:272
	ds_read_b128 v[70:73], v116 offset:512
	ds_read_b128 v[66:69], v116 offset:528
	ds_read_b128 v[62:65], v116 offset:768
	ds_read_b128 v[58:61], v116 offset:784
	ds_read_b128 v[46:49], v116 offset:1024
	ds_read_b128 v[42:45], v116 offset:1040
	v_add_f32_dpp v35, v36, v36 quad_perm:[1,0,3,2] row_mask:0xf bank_mask:0xf bound_ctrl:1
	v_add_f32_dpp v34, v34, v34 quad_perm:[1,0,3,2] row_mask:0xf bank_mask:0xf bound_ctrl:1
	v_add_u32_e32 v117, 0, v85
	v_add_f32_dpp v35, v35, v35 quad_perm:[2,3,0,1] row_mask:0xf bank_mask:0xf bound_ctrl:1
	v_add_f32_dpp v36, v34, v34 quad_perm:[2,3,0,1] row_mask:0xf bank_mask:0xf bound_ctrl:1
	ds_read2_b32 v[102:103], v117 offset1:32
	v_add_f32_dpp v34, v35, v35 row_half_mirror row_mask:0xf bank_mask:0xf bound_ctrl:1
	v_add_f32_dpp v36, v36, v36 row_half_mirror row_mask:0xf bank_mask:0xf bound_ctrl:1
	v_pk_mul_f32 v[38:39], v[22:23], v[34:35] op_sel_hi:[1,0]
	v_pk_mul_f32 v[22:23], v[22:23], v[36:37] op_sel_hi:[1,0]
	v_pk_mul_f32 v[40:41], v[24:25], v[34:35] op_sel_hi:[1,0]
	v_pk_mul_f32 v[24:25], v[24:25], v[36:37] op_sel_hi:[1,0]
	v_pk_mul_f32 v[104:105], v[18:19], v[34:35] op_sel_hi:[1,0]
	v_pk_mul_f32 v[18:19], v[18:19], v[36:37] op_sel_hi:[1,0]
	v_pk_mul_f32 v[34:35], v[20:21], v[34:35] op_sel_hi:[1,0]
	v_pk_mul_f32 v[20:21], v[20:21], v[36:37] op_sel_hi:[1,0]
	v_pk_fma_f32 v[36:37], v[30:31], v[82:83], v[38:39] op_sel_hi:[1,0,1]
	v_pk_fma_f32 v[22:23], v[30:31], v[84:85], v[22:23] op_sel_hi:[1,0,1]
	v_pk_fma_f32 v[30:31], v[32:33], v[82:83], v[40:41] op_sel_hi:[1,0,1]
	v_pk_fma_f32 v[24:25], v[32:33], v[84:85], v[24:25] op_sel_hi:[1,0,1]
	v_pk_fma_f32 v[32:33], v[26:27], v[82:83], v[104:105] op_sel_hi:[1,0,1]
	v_pk_fma_f32 v[18:19], v[26:27], v[84:85], v[18:19] op_sel_hi:[1,0,1]
	v_pk_fma_f32 v[26:27], v[28:29], v[82:83], v[34:35] op_sel_hi:[1,0,1]
	v_pk_fma_f32 v[20:21], v[28:29], v[84:85], v[20:21] op_sel_hi:[1,0,1]
	v_pk_fma_f32 v[86:87], v[6:7], v[86:87], v[36:37]
	v_pk_fma_f32 v[94:95], v[6:7], v[94:95], v[22:23]
	v_pk_fma_f32 v[90:91], v[2:3], v[90:91], v[32:33]
	v_pk_fma_f32 v[98:99], v[2:3], v[98:99], v[18:19]
	v_pk_fma_f32 v[88:89], v[8:9], v[88:89], v[30:31]
	v_pk_fma_f32 v[96:97], v[8:9], v[96:97], v[24:25]
	v_pk_fma_f32 v[92:93], v[4:5], v[92:93], v[26:27]
	v_pk_fma_f32 v[100:101], v[4:5], v[100:101], v[20:21]
	s_waitcnt lgkmcnt(12)
	v_pk_mul_f32 v[2:3], v[14:15], v[86:87]
	v_pk_mul_f32 v[4:5], v[14:15], v[94:95]
	s_waitcnt lgkmcnt(11)
	v_pk_mul_f32 v[6:7], v[10:11], v[90:91]
	v_pk_mul_f32 v[8:9], v[10:11], v[98:99]
	v_pk_fma_f32 v[2:3], v[16:17], v[88:89], v[2:3]
	v_pk_fma_f32 v[4:5], v[16:17], v[96:97], v[4:5]
	v_pk_fma_f32 v[6:7], v[12:13], v[92:93], v[6:7]
	v_pk_fma_f32 v[8:9], v[12:13], v[100:101], v[8:9]
	v_pk_add_f32 v[2:3], v[2:3], v[6:7]
	v_pk_add_f32 v[4:5], v[4:5], v[8:9]
	v_add_f32_e32 v2, v2, v3
	v_add_f32_e32 v3, v4, v5
	v_add_u32_e32 v115, 0x1c000, v1
	v_add_f32_dpp v2, v2, v2 quad_perm:[1,0,3,2] row_mask:0xf bank_mask:0xf bound_ctrl:1
	v_add_f32_dpp v3, v3, v3 quad_perm:[1,0,3,2] row_mask:0xf bank_mask:0xf bound_ctrl:1
	s_nop 0
	v_add_f32_dpp v2, v2, v2 quad_perm:[2,3,0,1] row_mask:0xf bank_mask:0xf bound_ctrl:1
	v_add_f32_dpp v3, v3, v3 quad_perm:[2,3,0,1] row_mask:0xf bank_mask:0xf bound_ctrl:1
	s_nop 0
	v_add_f32_dpp v2, v2, v2 row_half_mirror row_mask:0xf bank_mask:0xf bound_ctrl:1
	v_add_f32_dpp v3, v3, v3 row_half_mirror row_mask:0xf bank_mask:0xf bound_ctrl:1
	s_and_saveexec_b64 s[8:9], s[42:43]
	ds_write2_b32 v115, v2, v3 offset0:0 offset1:32
.LBB0_766:
	s_or_b64 exec, exec, s[8:9]
	s_waitcnt lgkmcnt(8)
	v_pk_mul_f32 v[104:105], v[78:79], v[86:87]
	v_pk_mul_f32 v[78:79], v[78:79], v[94:95]
	s_waitcnt lgkmcnt(7)
	v_pk_mul_f32 v[106:107], v[74:75], v[90:91]
	v_pk_mul_f32 v[74:75], v[74:75], v[98:99]
	v_pk_fma_f32 v[104:105], v[80:81], v[88:89], v[104:105]
	v_pk_fma_f32 v[78:79], v[80:81], v[96:97], v[78:79]
	v_pk_fma_f32 v[80:81], v[76:77], v[92:93], v[106:107]
	v_pk_fma_f32 v[74:75], v[76:77], v[100:101], v[74:75]
	v_pk_add_f32 v[76:77], v[104:105], v[80:81]
	v_pk_add_f32 v[74:75], v[78:79], v[74:75]
	v_add_f32_e32 v76, v76, v77
	v_add_f32_e32 v74, v74, v75
	s_waitcnt lgkmcnt(0)
	v_mov_b32_e32 v78, v103
	v_add_f32_dpp v75, v76, v76 quad_perm:[1,0,3,2] row_mask:0xf bank_mask:0xf bound_ctrl:1
	v_add_f32_dpp v74, v74, v74 quad_perm:[1,0,3,2] row_mask:0xf bank_mask:0xf bound_ctrl:1
	ds_read_b128 v[6:9], v116 offset:1536
	ds_read_b128 v[2:5], v116 offset:1552
	ds_read_b128 v[38:41], v116 offset:1792
	ds_read_b128 v[34:37], v116 offset:1808
	ds_read_b128 v[22:25], v116 offset:2048
	ds_read_b128 v[18:21], v116 offset:2064
	v_add_f32_dpp v75, v75, v75 quad_perm:[2,3,0,1] row_mask:0xf bank_mask:0xf bound_ctrl:1
	v_add_f32_dpp v76, v74, v74 quad_perm:[2,3,0,1] row_mask:0xf bank_mask:0xf bound_ctrl:1
	v_add_u32_e32 v10, 0x400, v117
	v_add_f32_dpp v74, v75, v75 row_half_mirror row_mask:0xf bank_mask:0xf bound_ctrl:1
	v_add_f32_dpp v76, v76, v76 row_half_mirror row_mask:0xf bank_mask:0xf bound_ctrl:1
	v_pk_mul_f32 v[80:81], v[70:71], v[74:75] op_sel_hi:[1,0]
	v_pk_mul_f32 v[70:71], v[70:71], v[76:77] op_sel_hi:[1,0]
	v_pk_mul_f32 v[104:105], v[72:73], v[74:75] op_sel_hi:[1,0]
	v_pk_mul_f32 v[72:73], v[72:73], v[76:77] op_sel_hi:[1,0]
	v_pk_mul_f32 v[106:107], v[66:67], v[74:75] op_sel_hi:[1,0]
	v_pk_mul_f32 v[66:67], v[66:67], v[76:77] op_sel_hi:[1,0]
	v_pk_mul_f32 v[74:75], v[68:69], v[74:75] op_sel_hi:[1,0]
	v_pk_mul_f32 v[68:69], v[68:69], v[76:77] op_sel_hi:[1,0]
	v_pk_fma_f32 v[76:77], v[62:63], v[102:103], v[80:81] op_sel_hi:[1,0,1]
	v_pk_fma_f32 v[62:63], v[62:63], v[78:79], v[70:71] op_sel_hi:[1,0,1]
	v_pk_fma_f32 v[70:71], v[64:65], v[102:103], v[104:105] op_sel_hi:[1,0,1]
	v_pk_fma_f32 v[64:65], v[64:65], v[78:79], v[72:73] op_sel_hi:[1,0,1]
	v_pk_fma_f32 v[72:73], v[58:59], v[102:103], v[106:107] op_sel_hi:[1,0,1]
	v_pk_fma_f32 v[58:59], v[58:59], v[78:79], v[66:67] op_sel_hi:[1,0,1]
	v_pk_fma_f32 v[66:67], v[60:61], v[102:103], v[74:75] op_sel_hi:[1,0,1]
	v_pk_fma_f32 v[60:61], v[60:61], v[78:79], v[68:69] op_sel_hi:[1,0,1]
	v_pk_fma_f32 v[102:103], v[54:55], v[86:87], v[76:77]
	v_pk_fma_f32 v[94:95], v[54:55], v[94:95], v[62:63]
	v_pk_fma_f32 v[106:107], v[50:51], v[90:91], v[72:73]
	v_pk_fma_f32 v[108:109], v[50:51], v[98:99], v[58:59]
	v_pk_fma_f32 v[104:105], v[56:57], v[88:89], v[70:71]
	v_pk_fma_f32 v[96:97], v[56:57], v[96:97], v[64:65]
	v_pk_fma_f32 v[110:111], v[52:53], v[92:93], v[66:67]
	v_pk_fma_f32 v[112:113], v[52:53], v[100:101], v[60:61]
	v_pk_mul_f32 v[50:51], v[46:47], v[102:103]
	v_pk_mul_f32 v[46:47], v[46:47], v[94:95]
	v_pk_mul_f32 v[52:53], v[42:43], v[106:107]
	v_pk_mul_f32 v[42:43], v[42:43], v[108:109]
	v_pk_fma_f32 v[50:51], v[48:49], v[104:105], v[50:51]
	v_pk_fma_f32 v[46:47], v[48:49], v[96:97], v[46:47]
	v_pk_fma_f32 v[48:49], v[44:45], v[110:111], v[52:53]
	v_pk_fma_f32 v[42:43], v[44:45], v[112:113], v[42:43]
	v_pk_add_f32 v[44:45], v[50:51], v[48:49]
	v_pk_add_f32 v[42:43], v[46:47], v[42:43]
	v_add_f32_e32 v44, v44, v45
	v_add_f32_e32 v42, v42, v43
	ds_read2_b32 v[82:83], v10 offset0:128 offset1:160
	ds_read_b128 v[30:33], v116 offset:2304
	ds_read_b128 v[26:29], v116 offset:2320
	ds_read_b128 v[14:17], v116 offset:2560
	ds_read_b128 v[10:13], v116 offset:2576
	v_add_f32_dpp v43, v44, v44 quad_perm:[1,0,3,2] row_mask:0xf bank_mask:0xf bound_ctrl:1
	v_add_f32_dpp v44, v42, v42 quad_perm:[1,0,3,2] row_mask:0xf bank_mask:0xf bound_ctrl:1
	s_waitcnt lgkmcnt(4)
	v_mov_b32_e32 v84, v83
	v_add_f32_dpp v42, v43, v43 quad_perm:[2,3,0,1] row_mask:0xf bank_mask:0xf bound_ctrl:1
	v_add_f32_dpp v43, v44, v44 quad_perm:[2,3,0,1] row_mask:0xf bank_mask:0xf bound_ctrl:1
	s_nop 0
	v_add_f32_dpp v42, v42, v42 row_half_mirror row_mask:0xf bank_mask:0xf bound_ctrl:1
	v_add_f32_dpp v43, v43, v43 row_half_mirror row_mask:0xf bank_mask:0xf bound_ctrl:1
	s_and_saveexec_b64 s[8:9], s[42:43]
	ds_write2_b32 v115, v42, v43 offset0:64 offset1:96
.LBB0_768:
	s_or_b64 exec, exec, s[8:9]
	v_pk_mul_f32 v[88:89], v[38:39], v[102:103]
	v_pk_mul_f32 v[90:91], v[38:39], v[94:95]
	v_pk_mul_f32 v[92:93], v[34:35], v[106:107]
	v_pk_mul_f32 v[98:99], v[34:35], v[108:109]
	v_pk_fma_f32 v[88:89], v[40:41], v[104:105], v[88:89]
	v_pk_fma_f32 v[90:91], v[40:41], v[96:97], v[90:91]
	v_pk_fma_f32 v[92:93], v[36:37], v[110:111], v[92:93]
	v_pk_fma_f32 v[98:99], v[36:37], v[112:113], v[98:99]
	v_add_u32_e32 v83, 0xc00, v117
	v_pk_add_f32 v[88:89], v[92:93], v[88:89]
	v_pk_add_f32 v[90:91], v[98:99], v[90:91]
	ds_read_b128 v[54:57], v116 offset:3072
	ds_read_b128 v[50:53], v116 offset:3088
	ds_read_b128 v[78:81], v116 offset:3328
	ds_read_b128 v[74:77], v116 offset:3344
	ds_read_b128 v[70:73], v116 offset:3584
	ds_read_b128 v[66:69], v116 offset:3600
	ds_read_b128 v[62:65], v116 offset:3840
	ds_read_b128 v[58:61], v116 offset:3856
	ds_read_b128 v[46:49], v116 offset:4096
	ds_read_b128 v[42:45], v116 offset:4112
	ds_read2_b32 v[86:87], v83 offset1:32
	v_add_f32_e32 v83, v88, v89
	v_add_f32_e32 v88, v90, v91
	s_nop 0
	v_add_f32_dpp v83, v83, v83 quad_perm:[1,0,3,2] row_mask:0xf bank_mask:0xf bound_ctrl:1
	v_add_f32_dpp v88, v88, v88 quad_perm:[1,0,3,2] row_mask:0xf bank_mask:0xf bound_ctrl:1
	s_nop 0
	v_add_f32_dpp v83, v83, v83 quad_perm:[2,3,0,1] row_mask:0xf bank_mask:0xf bound_ctrl:1
	v_add_f32_dpp v89, v88, v88 quad_perm:[2,3,0,1] row_mask:0xf bank_mask:0xf bound_ctrl:1
	s_nop 0
	v_add_f32_dpp v88, v83, v83 row_half_mirror row_mask:0xf bank_mask:0xf bound_ctrl:1
	v_add_f32_dpp v90, v89, v89 row_half_mirror row_mask:0xf bank_mask:0xf bound_ctrl:1
	v_pk_mul_f32 v[92:93], v[22:23], v[88:89] op_sel_hi:[1,0]
	v_pk_mul_f32 v[98:99], v[22:23], v[90:91] op_sel_hi:[1,0]
	v_pk_mul_f32 v[100:101], v[24:25], v[88:89] op_sel_hi:[1,0]
	v_pk_mul_f32 v[120:121], v[18:19], v[88:89] op_sel_hi:[1,0]
	v_pk_mul_f32 v[122:123], v[18:19], v[90:91] op_sel_hi:[1,0]
	v_pk_mul_f32 v[118:119], v[24:25], v[90:91] op_sel_hi:[1,0]
	v_pk_mul_f32 v[88:89], v[20:21], v[88:89] op_sel_hi:[1,0]
	v_pk_mul_f32 v[90:91], v[20:21], v[90:91] op_sel_hi:[1,0]
	s_waitcnt lgkmcnt(14)
	v_pk_fma_f32 v[92:93], v[30:31], v[82:83], v[92:93] op_sel_hi:[1,0,1]
	v_pk_fma_f32 v[98:99], v[30:31], v[84:85], v[98:99] op_sel_hi:[1,0,1]
	v_pk_fma_f32 v[100:101], v[32:33], v[82:83], v[100:101] op_sel_hi:[1,0,1]
	s_waitcnt lgkmcnt(13)
	v_pk_fma_f32 v[120:121], v[26:27], v[82:83], v[120:121] op_sel_hi:[1,0,1]
	v_pk_fma_f32 v[122:123], v[26:27], v[84:85], v[122:123] op_sel_hi:[1,0,1]
	v_pk_fma_f32 v[118:119], v[32:33], v[84:85], v[118:119] op_sel_hi:[1,0,1]
	v_pk_fma_f32 v[124:125], v[28:29], v[82:83], v[88:89] op_sel_hi:[1,0,1]
	v_pk_fma_f32 v[126:127], v[28:29], v[84:85], v[90:91] op_sel_hi:[1,0,1]
	v_pk_fma_f32 v[88:89], v[6:7], v[102:103], v[92:93]
	v_pk_fma_f32 v[90:91], v[6:7], v[94:95], v[98:99]
	v_pk_fma_f32 v[92:93], v[8:9], v[104:105], v[100:101]
	v_pk_fma_f32 v[98:99], v[2:3], v[106:107], v[120:121]
	v_pk_fma_f32 v[100:101], v[2:3], v[108:109], v[122:123]
	v_pk_fma_f32 v[96:97], v[8:9], v[96:97], v[118:119]
	v_pk_fma_f32 v[102:103], v[4:5], v[110:111], v[124:125]
	v_pk_fma_f32 v[104:105], v[4:5], v[112:113], v[126:127]
	s_waitcnt lgkmcnt(12)
	v_pk_mul_f32 v[94:95], v[14:15], v[88:89]
	v_pk_mul_f32 v[106:107], v[14:15], v[90:91]
	s_waitcnt lgkmcnt(11)
	v_pk_mul_f32 v[108:109], v[10:11], v[98:99]
	v_pk_mul_f32 v[110:111], v[10:11], v[100:101]
	v_pk_fma_f32 v[94:95], v[16:17], v[92:93], v[94:95]
	v_pk_fma_f32 v[106:107], v[16:17], v[96:97], v[106:107]
	v_pk_fma_f32 v[108:109], v[12:13], v[102:103], v[108:109]
	v_pk_fma_f32 v[110:111], v[12:13], v[104:105], v[110:111]
	v_pk_add_f32 v[94:95], v[94:95], v[108:109]
	v_pk_add_f32 v[106:107], v[106:107], v[110:111]
	v_add_f32_e32 v83, v94, v95
	v_add_f32_e32 v94, v106, v107
	s_nop 0
	v_add_f32_dpp v83, v83, v83 quad_perm:[1,0,3,2] row_mask:0xf bank_mask:0xf bound_ctrl:1
	v_add_f32_dpp v94, v94, v94 quad_perm:[1,0,3,2] row_mask:0xf bank_mask:0xf bound_ctrl:1
	s_nop 0
	v_add_f32_dpp v83, v83, v83 quad_perm:[2,3,0,1] row_mask:0xf bank_mask:0xf bound_ctrl:1
	v_add_f32_dpp v94, v94, v94 quad_perm:[2,3,0,1] row_mask:0xf bank_mask:0xf bound_ctrl:1
	s_nop 0
	v_add_f32_dpp v83, v83, v83 row_half_mirror row_mask:0xf bank_mask:0xf bound_ctrl:1
	v_add_f32_dpp v94, v94, v94 row_half_mirror row_mask:0xf bank_mask:0xf bound_ctrl:1
	s_and_saveexec_b64 s[8:9], s[42:43]
	ds_write2_b32 v115, v83, v94 offset0:128 offset1:160

; __device__ __forceinline__ void rwkv_unit(LAS unsigned char* lds, const LAS Params* PL, int b, int h, const int tid) {
;     ...
;             f32x4 Pd0, Pd1, Pn0, Pn1, Pe0, Pe1, Pk0, Pk1, Pr0, Pr1, Qd0, Qd1, Qn0, Qn1, Qe0, Qe1, Qk0, Qk1, Qr0, Qr1; float Pva, Pvb, Qva, Qvb;
;             RW_LV(P, 0);
; #pragma unroll 2
;             for (int tl = 0; tl < TC; tl += 2) {
;                 RW_LV(Q, tl + 1);
;                 RW_ROW2(P, tl * 64);
;                 if (tl + 2 < TC) RW_LV(P, tl + 2);
;                 RW_ROW2(Q, (tl + 1) * 64);
;             }
.LBB0_772:
	s_waitcnt lgkmcnt(8)
	v_pk_mul_f32 v[94:95], v[78:79], v[88:89]
	v_pk_mul_f32 v[78:79], v[78:79], v[90:91]
	s_waitcnt lgkmcnt(7)
	v_pk_mul_f32 v[106:107], v[74:75], v[98:99]
	v_pk_mul_f32 v[74:75], v[74:75], v[100:101]
	v_pk_fma_f32 v[94:95], v[80:81], v[92:93], v[94:95]
	v_pk_fma_f32 v[78:79], v[80:81], v[96:97], v[78:79]
	v_pk_fma_f32 v[80:81], v[76:77], v[102:103], v[106:107]
	v_pk_fma_f32 v[74:75], v[76:77], v[104:105], v[74:75]
	v_pk_add_f32 v[76:77], v[94:95], v[80:81]
	v_pk_add_f32 v[74:75], v[78:79], v[74:75]
	v_add_f32_e32 v76, v76, v77
	v_add_f32_e32 v74, v74, v75
	s_waitcnt lgkmcnt(0)
	v_mov_b32_e32 v78, v87
	v_add_f32_dpp v75, v76, v76 quad_perm:[1,0,3,2] row_mask:0xf bank_mask:0xf bound_ctrl:1
	v_add_f32_dpp v74, v74, v74 quad_perm:[1,0,3,2] row_mask:0xf bank_mask:0xf bound_ctrl:1
	s_nop 0
	v_add_f32_dpp v75, v75, v75 quad_perm:[2,3,0,1] row_mask:0xf bank_mask:0xf bound_ctrl:1
	v_add_f32_dpp v76, v74, v74 quad_perm:[2,3,0,1] row_mask:0xf bank_mask:0xf bound_ctrl:1
	s_nop 0
	v_add_f32_dpp v74, v75, v75 row_half_mirror row_mask:0xf bank_mask:0xf bound_ctrl:1
	v_add_f32_dpp v76, v76, v76 row_half_mirror row_mask:0xf bank_mask:0xf bound_ctrl:1
	v_pk_mul_f32 v[80:81], v[70:71], v[74:75] op_sel_hi:[1,0]
	v_pk_mul_f32 v[70:71], v[70:71], v[76:77] op_sel_hi:[1,0]
	v_pk_mul_f32 v[94:95], v[72:73], v[74:75] op_sel_hi:[1,0]
	v_pk_mul_f32 v[72:73], v[72:73], v[76:77] op_sel_hi:[1,0]
	v_pk_mul_f32 v[106:107], v[66:67], v[74:75] op_sel_hi:[1,0]
	v_pk_mul_f32 v[66:67], v[66:67], v[76:77] op_sel_hi:[1,0]
	v_pk_mul_f32 v[74:75], v[68:69], v[74:75] op_sel_hi:[1,0]
	v_pk_mul_f32 v[68:69], v[68:69], v[76:77] op_sel_hi:[1,0]
	v_pk_fma_f32 v[76:77], v[62:63], v[86:87], v[80:81] op_sel_hi:[1,0,1]
	v_pk_fma_f32 v[62:63], v[62:63], v[78:79], v[70:71] op_sel_hi:[1,0,1]
	v_pk_fma_f32 v[70:71], v[64:65], v[86:87], v[94:95] op_sel_hi:[1,0,1]
	v_pk_fma_f32 v[64:65], v[64:65], v[78:79], v[72:73] op_sel_hi:[1,0,1]
	v_pk_fma_f32 v[72:73], v[58:59], v[86:87], v[106:107] op_sel_hi:[1,0,1]
	v_pk_fma_f32 v[58:59], v[58:59], v[78:79], v[66:67] op_sel_hi:[1,0,1]
	v_pk_fma_f32 v[66:67], v[60:61], v[86:87], v[74:75] op_sel_hi:[1,0,1]
	v_pk_fma_f32 v[60:61], v[60:61], v[78:79], v[68:69] op_sel_hi:[1,0,1]
	v_pk_fma_f32 v[86:87], v[54:55], v[88:89], v[76:77]
	v_pk_fma_f32 v[94:95], v[54:55], v[90:91], v[62:63]
	v_pk_fma_f32 v[90:91], v[50:51], v[98:99], v[72:73]
	v_pk_fma_f32 v[98:99], v[50:51], v[100:101], v[58:59]
	v_pk_fma_f32 v[88:89], v[56:57], v[92:93], v[70:71]
	v_pk_fma_f32 v[96:97], v[56:57], v[96:97], v[64:65]
	v_pk_fma_f32 v[92:93], v[52:53], v[102:103], v[66:67]
	v_pk_fma_f32 v[100:101], v[52:53], v[104:105], v[60:61]
	v_pk_mul_f32 v[50:51], v[46:47], v[86:87]
	v_pk_mul_f32 v[46:47], v[46:47], v[94:95]
	v_pk_mul_f32 v[52:53], v[42:43], v[90:91]
	v_pk_mul_f32 v[42:43], v[42:43], v[98:99]
	v_pk_fma_f32 v[50:51], v[48:49], v[88:89], v[50:51]
	v_pk_fma_f32 v[46:47], v[48:49], v[96:97], v[46:47]
	v_pk_fma_f32 v[48:49], v[44:45], v[92:93], v[52:53]
	v_pk_fma_f32 v[42:43], v[44:45], v[100:101], v[42:43]
	v_pk_add_f32 v[44:45], v[50:51], v[48:49]
	v_pk_add_f32 v[42:43], v[46:47], v[42:43]
	v_add_f32_e32 v44, v44, v45
	v_add_f32_e32 v42, v42, v43
	s_nop 0
	v_add_f32_dpp v43, v44, v44 quad_perm:[1,0,3,2] row_mask:0xf bank_mask:0xf bound_ctrl:1
	v_add_f32_dpp v44, v42, v42 quad_perm:[1,0,3,2] row_mask:0xf bank_mask:0xf bound_ctrl:1
	s_nop 0
	v_add_f32_dpp v42, v43, v43 quad_perm:[2,3,0,1] row_mask:0xf bank_mask:0xf bound_ctrl:1
	v_add_f32_dpp v43, v44, v44 quad_perm:[2,3,0,1] row_mask:0xf bank_mask:0xf bound_ctrl:1
	s_nop 0
	v_add_f32_dpp v42, v42, v42 row_half_mirror row_mask:0xf bank_mask:0xf bound_ctrl:1
	v_add_f32_dpp v43, v43, v43 row_half_mirror row_mask:0xf bank_mask:0xf bound_ctrl:1
	s_and_saveexec_b64 s[16:17], s[42:43]
	ds_write2_b32 v115, v42, v43 offset0:192 offset1:224
	s_branch .LBB0_763
